# prologue phase 1: the 64 serialized adaLN partial-sum loads per unit issued in 4 batches
# speedup vs baseline: 1.0317x; 1.0041x over previous
; DI void phase_prologue_b(const Params& p, int bid, int nb) {
;     ...
;       for (int e = 0; e < 4; ++e) { const int col = e * 256 + lane * 4;
;         f32x4 a = *(const f32x4*)(p.b_ada + col), c = *(const f32x4*)(p.b_ada + 1024 + col);
;         for (int kc = 0; kc < 8; ++kc) { const float* mp = p.modp + ((size_t)(kc * 2 + 0) * 8 + b) * 6144; a += *(const f32x4*)(mp + col); c += *(const f32x4*)(mp + 1024 + col); }
;         sh[e] = a; sc[e] = c + 1.f; }
.LBB0_95:
	s_and_saveexec_b64 s[2:3], s[0:1]
	s_cbranch_execz .LBB0_90
	s_ashr_i32 s4, s62, 6
	v_readlane_b32 s8, v252, 17
	s_mul_hi_i32 s5, s4, 0x6000
	s_mulk_i32 s4, 0x6000
	v_readlane_b32 s14, v252, 23
	v_readlane_b32 s15, v252, 24
	s_add_u32 s4, s14, s4
	s_addc_u32 s5, s15, s5
	global_load_dwordx4 v[0:3], v[4:5], off
	global_load_dwordx4 v[20:23], v[6:7], off
	global_load_dwordx4 v[24:27], v54, s[4:5]
	s_add_u32 s6, s4, 0x1000
	s_addc_u32 s7, s5, 0
	v_readlane_b32 s9, v252, 18
	s_add_u32 s8, s4, 0x60000
	s_addc_u32 s9, s5, 0
	v_readlane_b32 s10, v252, 19
	v_readlane_b32 s11, v252, 20
	s_add_u32 s10, s4, 0x61000
	s_addc_u32 s11, s5, 0
	v_readlane_b32 s12, v252, 21
	v_readlane_b32 s13, v252, 22
	s_add_u32 s12, s4, 0xc0000
	s_addc_u32 s13, s5, 0
	s_add_u32 s14, s4, 0xc1000
	s_addc_u32 s15, s5, 0
	s_add_u32 s34, s4, 0x120000
	s_addc_u32 s35, s5, 0
	s_add_u32 s44, s4, 0x121000
	s_addc_u32 s45, s5, 0
	s_add_u32 s46, s4, 0x180000
	s_addc_u32 s47, s5, 0
	s_add_u32 s48, s4, 0x181000
	s_addc_u32 s49, s5, 0
	s_add_u32 s50, s4, 0x1e0000
	s_addc_u32 s51, s5, 0
	s_add_u32 s52, s4, 0x1e1000
	s_addc_u32 s53, s5, 0
	s_add_u32 s54, s4, 0x240000
	s_addc_u32 s55, s5, 0
	s_add_u32 s56, s4, 0x241000
	s_addc_u32 s57, s5, 0
	s_add_u32 s58, s4, 0x2a0000
	s_addc_u32 s59, s5, 0
	s_add_u32 s60, s4, 0x2a1000
	s_addc_u32 s61, s5, 0
	v_ashrrev_i32_e32 v17, 31, v16
	v_readlane_b32 s16, v252, 25
	v_readlane_b32 s17, v252, 26
	v_readlane_b32 s18, v252, 27
	v_readlane_b32 s19, v252, 28
	v_readlane_b32 s20, v252, 29
	v_readlane_b32 s21, v252, 30
	v_readlane_b32 s22, v252, 31
	v_readlane_b32 s23, v252, 32
	global_load_dwordx4 v[64:67], v54, s[6:7]
	global_load_dwordx4 v[68:71], v54, s[8:9]
	global_load_dwordx4 v[72:75], v54, s[10:11]
	global_load_dwordx4 v[76:79], v54, s[12:13]
	global_load_dwordx4 v[80:83], v54, s[14:15]
	global_load_dwordx4 v[84:87], v54, s[34:35]
	global_load_dwordx4 v[88:91], v54, s[44:45]
	global_load_dwordx4 v[92:95], v54, s[46:47]
	global_load_dwordx4 v[96:99], v54, s[48:49]
	global_load_dwordx4 v[100:103], v54, s[50:51]
	global_load_dwordx4 v[104:107], v54, s[52:53]
	global_load_dwordx4 v[108:111], v54, s[54:55]
	global_load_dwordx4 v[112:115], v54, s[56:57]
	global_load_dwordx4 v[116:119], v54, s[58:59]
	global_load_dwordx4 v[120:123], v54, s[60:61]
	s_waitcnt vmcnt(0)
	v_pk_add_f32 v[26:27], v[2:3], v[26:27]
	v_pk_add_f32 v[24:25], v[0:1], v[24:25]
	v_pk_add_f32 v[22:23], v[22:23], v[66:67]
	v_pk_add_f32 v[20:21], v[20:21], v[64:65]
	v_pk_add_f32 v[26:27], v[26:27], v[70:71]
	v_pk_add_f32 v[24:25], v[24:25], v[68:69]
	v_pk_add_f32 v[22:23], v[22:23], v[74:75]
	v_pk_add_f32 v[20:21], v[20:21], v[72:73]
	v_pk_add_f32 v[26:27], v[26:27], v[78:79]
	v_pk_add_f32 v[24:25], v[24:25], v[76:77]
	v_pk_add_f32 v[22:23], v[22:23], v[82:83]
	v_pk_add_f32 v[20:21], v[20:21], v[80:81]
	v_pk_add_f32 v[26:27], v[26:27], v[86:87]
	v_pk_add_f32 v[24:25], v[24:25], v[84:85]
	v_pk_add_f32 v[22:23], v[22:23], v[90:91]
	v_pk_add_f32 v[20:21], v[20:21], v[88:89]
	v_pk_add_f32 v[26:27], v[26:27], v[94:95]
	v_pk_add_f32 v[24:25], v[24:25], v[92:93]
	v_pk_add_f32 v[22:23], v[22:23], v[98:99]
	v_pk_add_f32 v[20:21], v[20:21], v[96:97]
	v_pk_add_f32 v[26:27], v[26:27], v[102:103]
	v_pk_add_f32 v[24:25], v[24:25], v[100:101]
	v_pk_add_f32 v[22:23], v[22:23], v[106:107]
	v_pk_add_f32 v[20:21], v[20:21], v[104:105]
	v_pk_add_f32 v[26:27], v[26:27], v[110:111]
	v_pk_add_f32 v[24:25], v[24:25], v[108:109]
	v_pk_add_f32 v[28:29], v[22:23], v[114:115]
	v_pk_add_f32 v[30:31], v[20:21], v[112:113]
	v_pk_add_f32 v[20:21], v[26:27], v[118:119]
	v_pk_add_f32 v[22:23], v[24:25], v[116:117]
	v_pk_add_f32 v[2:3], v[28:29], v[122:123]
	v_pk_add_f32 v[0:1], v[30:31], v[120:121]
	v_pk_add_f32 v[24:25], v[2:3], 1.0 op_sel_hi:[1,0]
	v_pk_add_f32 v[26:27], v[0:1], 1.0 op_sel_hi:[1,0]
	global_load_dwordx4 v[0:3], v[4:5], off offset:1024
	global_load_dwordx4 v[28:31], v[8:9], off
	global_load_dwordx4 v[32:35], v54, s[4:5] offset:1024
	global_load_dwordx4 v[64:67], v55, s[6:7]
	global_load_dwordx4 v[68:71], v55, s[8:9]
	global_load_dwordx4 v[72:75], v55, s[10:11]
	global_load_dwordx4 v[76:79], v55, s[12:13]
	global_load_dwordx4 v[80:83], v55, s[14:15]
	global_load_dwordx4 v[84:87], v55, s[34:35]
	global_load_dwordx4 v[88:91], v55, s[44:45]
	global_load_dwordx4 v[92:95], v55, s[46:47]
	global_load_dwordx4 v[96:99], v55, s[48:49]
	global_load_dwordx4 v[100:103], v55, s[50:51]
	global_load_dwordx4 v[104:107], v55, s[52:53]
	global_load_dwordx4 v[108:111], v55, s[54:55]
	global_load_dwordx4 v[112:115], v55, s[56:57]
	global_load_dwordx4 v[116:119], v55, s[58:59]
	global_load_dwordx4 v[120:123], v55, s[60:61]
	s_waitcnt vmcnt(0)
; DI void phase_prologue_b(const Params& p, int bid, int nb) {
;     ...
;       for (int e = 0; e < 4; ++e) { const int col = e * 256 + lane * 4;
;         f32x4 a = *(const f32x4*)(p.b_ada + col), c = *(const f32x4*)(p.b_ada + 1024 + col);
;         for (int kc = 0; kc < 8; ++kc) { const float* mp = p.modp + ((size_t)(kc * 2 + 0) * 8 + b) * 6144; a += *(const f32x4*)(mp + col); c += *(const f32x4*)(mp + 1024 + col); }
;         sh[e] = a; sc[e] = c + 1.f; }
;       for (int r = wid; r < 64; r += 8) { const size_t row = (size_t)(row0 + r);
	v_pk_add_f32 v[34:35], v[2:3], v[34:35]
	v_pk_add_f32 v[32:33], v[0:1], v[32:33]
	v_pk_add_f32 v[30:31], v[30:31], v[66:67]
	v_pk_add_f32 v[28:29], v[28:29], v[64:65]
	v_pk_add_f32 v[34:35], v[34:35], v[70:71]
	v_pk_add_f32 v[32:33], v[32:33], v[68:69]
	v_pk_add_f32 v[30:31], v[30:31], v[74:75]
	v_pk_add_f32 v[28:29], v[28:29], v[72:73]
	v_pk_add_f32 v[34:35], v[34:35], v[78:79]
	v_pk_add_f32 v[32:33], v[32:33], v[76:77]
	v_pk_add_f32 v[30:31], v[30:31], v[82:83]
	v_pk_add_f32 v[28:29], v[28:29], v[80:81]
	v_pk_add_f32 v[34:35], v[34:35], v[86:87]
	v_pk_add_f32 v[32:33], v[32:33], v[84:85]
	v_pk_add_f32 v[30:31], v[30:31], v[90:91]
	v_pk_add_f32 v[28:29], v[28:29], v[88:89]
	v_pk_add_f32 v[34:35], v[34:35], v[94:95]
	v_pk_add_f32 v[32:33], v[32:33], v[92:93]
	v_pk_add_f32 v[30:31], v[30:31], v[98:99]
	v_pk_add_f32 v[28:29], v[28:29], v[96:97]
	v_pk_add_f32 v[34:35], v[34:35], v[102:103]
	v_pk_add_f32 v[32:33], v[32:33], v[100:101]
	v_pk_add_f32 v[30:31], v[30:31], v[106:107]
	v_pk_add_f32 v[28:29], v[28:29], v[104:105]
	v_pk_add_f32 v[34:35], v[34:35], v[110:111]
	v_pk_add_f32 v[32:33], v[32:33], v[108:109]
	v_pk_add_f32 v[36:37], v[30:31], v[114:115]
	v_pk_add_f32 v[38:39], v[28:29], v[112:113]
	v_pk_add_f32 v[28:29], v[34:35], v[118:119]
	v_pk_add_f32 v[30:31], v[32:33], v[116:117]
	v_pk_add_f32 v[2:3], v[36:37], v[122:123]
	v_pk_add_f32 v[0:1], v[38:39], v[120:121]
	v_pk_add_f32 v[32:33], v[2:3], 1.0 op_sel_hi:[1,0]
	v_pk_add_f32 v[34:35], v[0:1], 1.0 op_sel_hi:[1,0]
	global_load_dwordx4 v[0:3], v[4:5], off offset:2048
	global_load_dwordx4 v[36:39], v[10:11], off
	global_load_dwordx4 v[40:43], v54, s[4:5] offset:2048
	global_load_dwordx4 v[64:67], v56, s[6:7]
	global_load_dwordx4 v[68:71], v56, s[8:9]
	global_load_dwordx4 v[72:75], v56, s[10:11]
	global_load_dwordx4 v[76:79], v56, s[12:13]
	global_load_dwordx4 v[80:83], v56, s[14:15]
	global_load_dwordx4 v[84:87], v56, s[34:35]
	global_load_dwordx4 v[88:91], v56, s[44:45]
	global_load_dwordx4 v[92:95], v56, s[46:47]
	global_load_dwordx4 v[96:99], v56, s[48:49]
	global_load_dwordx4 v[100:103], v56, s[50:51]
	global_load_dwordx4 v[104:107], v56, s[52:53]
	global_load_dwordx4 v[108:111], v56, s[54:55]
	global_load_dwordx4 v[112:115], v56, s[56:57]
	global_load_dwordx4 v[116:119], v56, s[58:59]
	global_load_dwordx4 v[120:123], v56, s[60:61]
	s_waitcnt vmcnt(0)
	v_pk_add_f32 v[42:43], v[2:3], v[42:43]
	v_pk_add_f32 v[40:41], v[0:1], v[40:41]
	v_pk_add_f32 v[38:39], v[38:39], v[66:67]
	v_pk_add_f32 v[36:37], v[36:37], v[64:65]
	v_pk_add_f32 v[42:43], v[42:43], v[70:71]
	v_pk_add_f32 v[40:41], v[40:41], v[68:69]
	v_pk_add_f32 v[38:39], v[38:39], v[74:75]
	v_pk_add_f32 v[36:37], v[36:37], v[72:73]
	v_pk_add_f32 v[42:43], v[42:43], v[78:79]
	v_pk_add_f32 v[40:41], v[40:41], v[76:77]
	v_pk_add_f32 v[38:39], v[38:39], v[82:83]
	v_pk_add_f32 v[36:37], v[36:37], v[80:81]
	v_pk_add_f32 v[42:43], v[42:43], v[86:87]
	v_pk_add_f32 v[40:41], v[40:41], v[84:85]
	v_pk_add_f32 v[38:39], v[38:39], v[90:91]
	v_pk_add_f32 v[36:37], v[36:37], v[88:89]
	v_pk_add_f32 v[42:43], v[42:43], v[94:95]
	v_pk_add_f32 v[40:41], v[40:41], v[92:93]
	v_pk_add_f32 v[38:39], v[38:39], v[98:99]
	v_pk_add_f32 v[36:37], v[36:37], v[96:97]
	v_pk_add_f32 v[42:43], v[42:43], v[102:103]
	v_pk_add_f32 v[40:41], v[40:41], v[100:101]
	v_pk_add_f32 v[38:39], v[38:39], v[106:107]
	v_pk_add_f32 v[36:37], v[36:37], v[104:105]
	v_pk_add_f32 v[42:43], v[42:43], v[110:111]
	v_pk_add_f32 v[40:41], v[40:41], v[108:109]
	v_pk_add_f32 v[44:45], v[38:39], v[114:115]
	v_pk_add_f32 v[46:47], v[36:37], v[112:113]
	v_pk_add_f32 v[36:37], v[42:43], v[118:119]
	v_pk_add_f32 v[38:39], v[40:41], v[116:117]
	v_pk_add_f32 v[2:3], v[44:45], v[122:123]
	v_pk_add_f32 v[0:1], v[46:47], v[120:121]
	v_pk_add_f32 v[40:41], v[2:3], 1.0 op_sel_hi:[1,0]
	v_pk_add_f32 v[42:43], v[0:1], 1.0 op_sel_hi:[1,0]
	global_load_dwordx4 v[0:3], v[4:5], off offset:3072
	global_load_dwordx4 v[44:47], v[12:13], off
	global_load_dwordx4 v[48:51], v54, s[4:5] offset:3072
	s_mov_b64 s[4:5], 0
	global_load_dwordx4 v[64:67], v57, s[6:7]
	global_load_dwordx4 v[68:71], v57, s[8:9]
	global_load_dwordx4 v[72:75], v57, s[10:11]
	global_load_dwordx4 v[76:79], v57, s[12:13]
	global_load_dwordx4 v[80:83], v57, s[14:15]
	global_load_dwordx4 v[84:87], v57, s[34:35]
	global_load_dwordx4 v[88:91], v57, s[44:45]
	global_load_dwordx4 v[92:95], v57, s[46:47]
	global_load_dwordx4 v[96:99], v57, s[48:49]
	global_load_dwordx4 v[100:103], v57, s[50:51]
	global_load_dwordx4 v[104:107], v57, s[52:53]
	global_load_dwordx4 v[108:111], v57, s[54:55]
	global_load_dwordx4 v[112:115], v57, s[56:57]
	global_load_dwordx4 v[116:119], v57, s[58:59]
	global_load_dwordx4 v[120:123], v57, s[60:61]
	s_waitcnt vmcnt(0)
	v_pk_add_f32 v[50:51], v[2:3], v[50:51]
	v_pk_add_f32 v[48:49], v[0:1], v[48:49]
	v_pk_add_f32 v[46:47], v[46:47], v[66:67]
	v_pk_add_f32 v[44:45], v[44:45], v[64:65]
	v_pk_add_f32 v[50:51], v[50:51], v[70:71]
	v_pk_add_f32 v[48:49], v[48:49], v[68:69]
	v_pk_add_f32 v[46:47], v[46:47], v[74:75]
	v_pk_add_f32 v[44:45], v[44:45], v[72:73]
	v_pk_add_f32 v[50:51], v[50:51], v[78:79]
	v_pk_add_f32 v[48:49], v[48:49], v[76:77]
	v_pk_add_f32 v[46:47], v[46:47], v[82:83]
	v_pk_add_f32 v[44:45], v[44:45], v[80:81]
	v_pk_add_f32 v[50:51], v[50:51], v[86:87]
	v_pk_add_f32 v[48:49], v[48:49], v[84:85]
	v_pk_add_f32 v[46:47], v[46:47], v[90:91]
	v_pk_add_f32 v[44:45], v[44:45], v[88:89]
	v_pk_add_f32 v[50:51], v[50:51], v[94:95]
	v_pk_add_f32 v[48:49], v[48:49], v[92:93]
	v_pk_add_f32 v[46:47], v[46:47], v[98:99]
	v_pk_add_f32 v[44:45], v[44:45], v[96:97]
	v_pk_add_f32 v[50:51], v[50:51], v[102:103]
	v_pk_add_f32 v[48:49], v[48:49], v[100:101]
	v_pk_add_f32 v[46:47], v[46:47], v[106:107]
	v_pk_add_f32 v[44:45], v[44:45], v[104:105]
	v_pk_add_f32 v[58:59], v[50:51], v[110:111]
	v_pk_add_f32 v[60:61], v[48:49], v[108:109]
	v_pk_add_f32 v[48:49], v[46:47], v[114:115]
	v_pk_add_f32 v[50:51], v[44:45], v[112:113]
	v_pk_add_f32 v[44:45], v[58:59], v[118:119]
	v_pk_add_f32 v[46:47], v[60:61], v[116:117]
	v_pk_add_f32 v[2:3], v[48:49], v[122:123]
	v_pk_add_f32 v[48:49], v[50:51], v[120:121]
	v_pk_add_f32 v[0:1], v[2:3], 1.0 op_sel_hi:[1,0]
	v_pk_add_f32 v[2:3], v[48:49], 1.0 op_sel_hi:[1,0]
	v_lshlrev_b64 v[48:49], 12, v[16:17]
	v_lshlrev_b64 v[50:51], 11, v[16:17]
	v_lshl_add_u64 v[48:49], v[14:15], 0, v[48:49]
	v_lshl_add_u64 v[50:51], v[18:19], 0, v[50:51]
	v_mov_b32_e32 v17, v53
